# v61 + NSA block-selection rank loops: the four ds_read2 of each 8-candidate iteration issued up front into spare registers with counted lgkmcnt waits (4 LDS round trips -> 1 per iteration)
# speedup vs baseline: 1.0034x; 1.0026x over previous
; DI void phase_attn_nsa(const Params& P, bf16_t* og, unsigned char* smem, int L, int G) {
;     ...
;     for (int pss = 0; pss < 4; ++pss) {
;       const int pair = pss * 256 + tid, q = pair >> 5, j = pair & 31;
;       const int tq = t0 + q, cur = tq >> 6;
;       const bool forced = (j == 0) || (j == cur) || (j == cur - 1);
;       const int nf = cur >= 2 ? 3 : cur + 1;
;       const int need = 8 - nf;
;       const bool cand = (j >= 1) && (j <= cur - 2);
;       const float sj = scoreL[q * 33 + j];
;       int rank = 0;
;       for (int j2 = 1; j2 <= cur - 2; ++j2) {
;         const float s2v = scoreL[q * 33 + j2];
;         rank += (s2v > sj || (s2v == sj && j2 < j)) ? 1 : 0;
;       }
.LBB0_1282:
	ds_read2_b32 v[40:41], v0 offset1:1
	ds_read2_b32 v[248:249], v0 offset0:2 offset1:3
	ds_read2_b32 v[250:251], v0 offset0:4 offset1:5
	ds_read2_b32 v[252:253], v0 offset0:6 offset1:7
	v_cmp_lt_u32_e64 s[6:7], s12, v118
	v_cmp_lt_u32_e64 s[8:9], s13, v35
	s_add_i32 s15, s15, 8
	s_add_i32 s16, s16, -4
	s_waitcnt lgkmcnt(3)
	v_cmp_gt_f32_e32 vcc, v41, v34
	v_cmp_gt_f32_e64 s[0:1], v40, v34
	v_cmp_eq_f32_e64 s[2:3], v40, v34
	v_cmp_eq_f32_e64 s[4:5], v41, v34
	s_and_b64 s[4:5], s[4:5], s[8:9]
	s_and_b64 s[2:3], s[2:3], s[6:7]
	s_or_b64 s[0:1], s[0:1], s[2:3]
	s_or_b64 s[2:3], vcc, s[4:5]
	s_add_i32 s8, s12, 2
	s_add_i32 s6, s13, 2
	v_cndmask_b32_e64 v42, 0, 1, s[2:3]
	s_waitcnt lgkmcnt(2)
	v_cmp_eq_f32_e64 s[2:3], v249, v34
	v_cmp_eq_f32_e64 s[4:5], v248, v34
	v_cmp_lt_u32_e64 s[6:7], s6, v35
	v_cmp_lt_u32_e64 s[8:9], s8, v118
	v_cndmask_b32_e64 v45, 0, 1, s[0:1]
	v_cmp_gt_f32_e32 vcc, v248, v34
	v_cmp_gt_f32_e64 s[0:1], v249, v34
	s_and_b64 s[4:5], s[4:5], s[8:9]
	s_and_b64 s[2:3], s[2:3], s[6:7]
	s_or_b64 s[0:1], s[0:1], s[2:3]
	s_or_b64 vcc, vcc, s[4:5]
	v_addc_co_u32_e32 v40, vcc, v36, v45, vcc
	v_addc_co_u32_e64 v41, vcc, v37, v42, s[0:1]
	s_add_i32 s8, s12, 4
	s_add_i32 s6, s13, 4
	v_cmp_lt_u32_e64 s[6:7], s6, v35
	v_cmp_lt_u32_e64 s[8:9], s8, v118
	s_waitcnt lgkmcnt(1)
	v_cmp_gt_f32_e32 vcc, v250, v34
	v_cmp_gt_f32_e64 s[0:1], v251, v34
	v_cmp_eq_f32_e64 s[2:3], v251, v34
	v_cmp_eq_f32_e64 s[4:5], v250, v34
	s_and_b64 s[4:5], s[4:5], s[8:9]
	s_and_b64 s[2:3], s[2:3], s[6:7]
	s_or_b64 s[0:1], s[0:1], s[2:3]
	s_or_b64 s[2:3], vcc, s[4:5]
	s_add_i32 s8, s13, 6
	s_add_i32 s6, s12, 6
	v_cndmask_b32_e64 v42, 0, 1, s[2:3]
	s_waitcnt lgkmcnt(0)
	v_cmp_eq_f32_e64 s[2:3], v252, v34
	v_cmp_eq_f32_e64 s[4:5], v253, v34
	v_cmp_lt_u32_e64 s[6:7], s6, v118
	v_cmp_lt_u32_e64 s[8:9], s8, v35
	v_cndmask_b32_e64 v45, 0, 1, s[0:1]
	v_cmp_gt_f32_e32 vcc, v253, v34
	v_cmp_gt_f32_e64 s[0:1], v252, v34
	s_and_b64 s[4:5], s[4:5], s[8:9]
	s_and_b64 s[2:3], s[2:3], s[6:7]
	s_or_b64 s[0:1], s[0:1], s[2:3]
	s_or_b64 vcc, vcc, s[4:5]
	s_add_i32 s13, s13, 8
	s_add_i32 s12, s12, 8
	v_addc_co_u32_e32 v37, vcc, v41, v45, vcc
	v_addc_co_u32_e64 v36, vcc, v40, v42, s[0:1]
	v_add_u32_e32 v0, 32, v0
	s_cmp_lg_u32 s16, 0
	s_cbranch_scc1 .LBB0_1282
	s_and_b32 s0, s14, 3
	s_cmp_eq_u32 s0, 0
	s_cbranch_scc0 .LBB0_1286
	s_branch .LBB0_1288

; DI void phase_attn_nsa(const Params& P, bf16_t* og, unsigned char* smem, int L, int G) {
;     ...
;     for (int pss = 0; pss < 4; ++pss) {
;       const int pair = pss * 256 + tid, q = pair >> 5, j = pair & 31;
;       const int tq = t0 + q, cur = tq >> 6;
;       const bool forced = (j == 0) || (j == cur) || (j == cur - 1);
;       const int nf = cur >= 2 ? 3 : cur + 1;
;       const int need = 8 - nf;
;       const bool cand = (j >= 1) && (j <= cur - 2);
;       const float sj = scoreL[q * 33 + j];
;       int rank = 0;
;       for (int j2 = 1; j2 <= cur - 2; ++j2) {
;         const float s2v = scoreL[q * 33 + j2];
;         rank += (s2v > sj || (s2v == sj && j2 < j)) ? 1 : 0;
;       }
.LBB0_1298:
	ds_read2_b32 v[48:49], v0 offset1:1
	ds_read2_b32 v[248:249], v0 offset0:2 offset1:3
	ds_read2_b32 v[250:251], v0 offset0:4 offset1:5
	ds_read2_b32 v[252:253], v0 offset0:6 offset1:7
	v_cmp_lt_u32_e64 s[6:7], s18, v118
	v_cmp_lt_u32_e64 s[10:11], s19, v35
	s_add_i32 s25, s25, 8
	s_add_i32 s26, s26, -4
	s_waitcnt lgkmcnt(3)
	v_cmp_gt_f32_e32 vcc, v49, v47
	v_cmp_gt_f32_e64 s[0:1], v48, v47
	v_cmp_eq_f32_e64 s[2:3], v48, v47
	v_cmp_eq_f32_e64 s[4:5], v49, v47
	s_and_b64 s[4:5], s[4:5], s[10:11]
	s_and_b64 s[2:3], s[2:3], s[6:7]
	s_or_b64 s[0:1], s[0:1], s[2:3]
	s_or_b64 s[2:3], vcc, s[4:5]
	s_add_i32 s10, s18, 2
	s_add_i32 s6, s19, 2
	v_cndmask_b32_e64 v50, 0, 1, s[2:3]
	s_waitcnt lgkmcnt(2)
	v_cmp_eq_f32_e64 s[2:3], v249, v47
	v_cmp_eq_f32_e64 s[4:5], v248, v47
	v_cmp_lt_u32_e64 s[6:7], s6, v35
	v_cmp_lt_u32_e64 s[10:11], s10, v118
	v_cndmask_b32_e64 v51, 0, 1, s[0:1]
	v_cmp_gt_f32_e32 vcc, v248, v47
	v_cmp_gt_f32_e64 s[0:1], v249, v47
	s_and_b64 s[4:5], s[4:5], s[10:11]
	s_and_b64 s[2:3], s[2:3], s[6:7]
	s_or_b64 s[0:1], s[0:1], s[2:3]
	s_or_b64 vcc, vcc, s[4:5]
	v_addc_co_u32_e32 v48, vcc, v36, v51, vcc
	v_addc_co_u32_e64 v49, vcc, v37, v50, s[0:1]
	s_add_i32 s10, s18, 4
	s_add_i32 s6, s19, 4
	v_cmp_lt_u32_e64 s[6:7], s6, v35
	v_cmp_lt_u32_e64 s[10:11], s10, v118
	s_waitcnt lgkmcnt(1)
	v_cmp_gt_f32_e32 vcc, v250, v47
	v_cmp_gt_f32_e64 s[0:1], v251, v47
	v_cmp_eq_f32_e64 s[2:3], v251, v47
	v_cmp_eq_f32_e64 s[4:5], v250, v47
	s_and_b64 s[4:5], s[4:5], s[10:11]
	s_and_b64 s[2:3], s[2:3], s[6:7]
	s_or_b64 s[0:1], s[0:1], s[2:3]
	s_or_b64 s[2:3], vcc, s[4:5]
	s_add_i32 s10, s19, 6
	s_add_i32 s6, s18, 6
	v_cndmask_b32_e64 v50, 0, 1, s[2:3]
	s_waitcnt lgkmcnt(0)
	v_cmp_eq_f32_e64 s[2:3], v252, v47
	v_cmp_eq_f32_e64 s[4:5], v253, v47
	v_cmp_lt_u32_e64 s[6:7], s6, v118
	v_cmp_lt_u32_e64 s[10:11], s10, v35
	v_cndmask_b32_e64 v51, 0, 1, s[0:1]
	v_cmp_gt_f32_e32 vcc, v253, v47
	v_cmp_gt_f32_e64 s[0:1], v252, v47
	s_and_b64 s[4:5], s[4:5], s[10:11]
	s_and_b64 s[2:3], s[2:3], s[6:7]
	s_or_b64 s[0:1], s[0:1], s[2:3]
	s_or_b64 vcc, vcc, s[4:5]
	s_add_i32 s19, s19, 8
	s_add_i32 s18, s18, 8
	v_addc_co_u32_e32 v37, vcc, v49, v51, vcc
	v_addc_co_u32_e64 v36, vcc, v48, v50, s[0:1]
	v_add_u32_e32 v0, 32, v0
	s_cmp_lg_u32 s26, 0
	s_cbranch_scc1 .LBB0_1298
	s_and_b32 s0, s24, 3
	s_cmp_eq_u32 s0, 0
	s_cbranch_scc0 .LBB0_1302
	s_branch .LBB0_1304

; DI void phase_attn_nsa(const Params& P, bf16_t* og, unsigned char* smem, int L, int G) {
;     ...
;     for (int pss = 0; pss < 4; ++pss) {
;       const int pair = pss * 256 + tid, q = pair >> 5, j = pair & 31;
;       const int tq = t0 + q, cur = tq >> 6;
;       const bool forced = (j == 0) || (j == cur) || (j == cur - 1);
;       const int nf = cur >= 2 ? 3 : cur + 1;
;       const int need = 8 - nf;
;       const bool cand = (j >= 1) && (j <= cur - 2);
;       const float sj = scoreL[q * 33 + j];
;       int rank = 0;
;       for (int j2 = 1; j2 <= cur - 2; ++j2) {
;         const float s2v = scoreL[q * 33 + j2];
;         rank += (s2v > sj || (s2v == sj && j2 < j)) ? 1 : 0;
;       }
.LBB0_1330:
	ds_read2_b32 v[48:49], v0 offset1:1
	ds_read2_b32 v[248:249], v0 offset0:2 offset1:3
	ds_read2_b32 v[250:251], v0 offset0:4 offset1:5
	ds_read2_b32 v[252:253], v0 offset0:6 offset1:7
	v_cmp_lt_u32_e64 s[6:7], s12, v118
	v_cmp_lt_u32_e64 s[10:11], s13, v35
	s_add_i32 s19, s19, 8
	s_add_i32 s24, s24, -4
	s_waitcnt lgkmcnt(3)
	v_cmp_gt_f32_e32 vcc, v49, v44
	v_cmp_gt_f32_e64 s[0:1], v48, v44
	v_cmp_eq_f32_e64 s[2:3], v48, v44
	v_cmp_eq_f32_e64 s[4:5], v49, v44
	s_and_b64 s[4:5], s[4:5], s[10:11]
	s_and_b64 s[2:3], s[2:3], s[6:7]
	s_or_b64 s[0:1], s[0:1], s[2:3]
	s_or_b64 s[2:3], vcc, s[4:5]
	s_add_i32 s10, s12, 2
	s_add_i32 s6, s13, 2
	v_cndmask_b32_e64 v43, 0, 1, s[2:3]
	s_waitcnt lgkmcnt(2)
	v_cmp_eq_f32_e64 s[2:3], v249, v44
	v_cmp_eq_f32_e64 s[4:5], v248, v44
	v_cmp_lt_u32_e64 s[6:7], s6, v35
	v_cmp_lt_u32_e64 s[10:11], s10, v118
	v_cndmask_b32_e64 v47, 0, 1, s[0:1]
	v_cmp_gt_f32_e32 vcc, v248, v44
	v_cmp_gt_f32_e64 s[0:1], v249, v44
	s_and_b64 s[4:5], s[4:5], s[10:11]
	s_and_b64 s[2:3], s[2:3], s[6:7]
	s_or_b64 s[0:1], s[0:1], s[2:3]
	s_or_b64 vcc, vcc, s[4:5]
	v_addc_co_u32_e32 v47, vcc, v36, v47, vcc
	v_addc_co_u32_e64 v43, vcc, v37, v43, s[0:1]
	s_add_i32 s10, s12, 4
	s_add_i32 s6, s13, 4
	v_cmp_lt_u32_e64 s[6:7], s6, v35
	v_cmp_lt_u32_e64 s[10:11], s10, v118
	s_waitcnt lgkmcnt(1)
	v_cmp_gt_f32_e32 vcc, v250, v44
	v_cmp_gt_f32_e64 s[0:1], v251, v44
	v_cmp_eq_f32_e64 s[2:3], v251, v44
	v_cmp_eq_f32_e64 s[4:5], v250, v44
	s_and_b64 s[4:5], s[4:5], s[10:11]
	s_and_b64 s[2:3], s[2:3], s[6:7]
	s_or_b64 s[0:1], s[0:1], s[2:3]
	s_or_b64 s[2:3], vcc, s[4:5]
	s_add_i32 s10, s13, 6
	s_add_i32 s6, s12, 6
	v_cndmask_b32_e64 v48, 0, 1, s[2:3]
	s_waitcnt lgkmcnt(0)
	v_cmp_eq_f32_e64 s[2:3], v252, v44
	v_cmp_eq_f32_e64 s[4:5], v253, v44
	v_cmp_lt_u32_e64 s[6:7], s6, v118
	v_cmp_lt_u32_e64 s[10:11], s10, v35
	v_cndmask_b32_e64 v49, 0, 1, s[0:1]
	v_cmp_gt_f32_e32 vcc, v253, v44
	v_cmp_gt_f32_e64 s[0:1], v252, v44
	s_and_b64 s[4:5], s[4:5], s[10:11]
	s_and_b64 s[2:3], s[2:3], s[6:7]
	s_or_b64 s[0:1], s[0:1], s[2:3]
	s_or_b64 vcc, vcc, s[4:5]
	s_add_i32 s13, s13, 8
	s_add_i32 s12, s12, 8
	v_addc_co_u32_e32 v37, vcc, v43, v49, vcc
	v_addc_co_u32_e64 v36, vcc, v47, v48, s[0:1]
	v_add_u32_e32 v0, 32, v0
	s_cmp_lg_u32 s24, 0
	s_cbranch_scc1 .LBB0_1330
	s_and_b32 s0, s18, 3
	s_cmp_eq_u32 s0, 0
	s_cbranch_scc0 .LBB0_1334
	s_branch .LBB0_1336
